# g1/gin epilogue: s_waitcnt vmcnt(0) relaxed to vmcnt(8) so next-unit DMA prefetches land during the epilogue (stat loads already retired)
# baseline (speedup 1.0000x reference)
.Lgin_epi:
	s_setprio 0
	s_nop 0
	s_nop 0
	s_nop 0
	s_nop 0
	s_nop 0
	s_nop 0
	s_waitcnt vmcnt(8)
	v_fmamk_f32 v130, v156, 0x3a800000, v235
	v_mul_f32_e32 v131, 0x4b800000, v130
	v_cmp_gt_f32_e32 vcc, s86, v130
	s_cmp_lt_i32 s40, 4
	s_cselect_b64 s[14:15], -1, 0
	v_cndmask_b32_e32 v130, v130, v131, vcc
	v_rsq_f32_e32 v130, v130
	s_cmp_gt_i32 s40, 3
	v_mul_f32_e32 v131, 0x45800000, v130
	v_cndmask_b32_e32 v156, v130, v131, vcc
	v_pk_mul_f32 v[126:127], v[156:157], v[126:127] op_sel_hi:[0,1]
	v_pk_mul_f32 v[124:125], v[156:157], v[124:125] op_sel_hi:[0,1]
	v_pk_mul_f32 v[158:159], v[156:157], v[122:123] op_sel_hi:[0,1]
	v_pk_mul_f32 v[160:161], v[156:157], v[120:121] op_sel_hi:[0,1]
	s_cbranch_scc1 .LBB0_274
	v_mul_f32_e32 v121, 0x3d372713, v160
	v_mul_f32_e32 v121, v160, v121
	v_fma_f32 v121, v160, v121, v160
	v_mul_f32_e32 v121, 0x3fcc422a, v121
	v_mul_f32_e32 v121, 0xbfb8aa3b, v121
	v_exp_f32_e32 v121, v121
	v_mul_f32_e32 v120, 0x3d372713, v124
	v_mul_f32_e32 v120, v124, v120
	v_mov_b32_e32 v123, v125
	v_add_f32_e32 v121, 1.0, v121
	v_rcp_f32_e32 v122, v121
	v_mul_f32_e32 v121, 0x3d372713, v125
	v_mul_f32_e32 v121, v125, v121
	v_fma_f32 v120, v124, v120, v124
	v_fmac_f32_e32 v123, v123, v121
	v_mul_f32_e32 v120, 0x3fcc422a, v120
	v_mul_f32_e32 v121, 0x3fcc422a, v123
	v_mul_f32_e32 v120, 0xbfb8aa3b, v120
	v_mul_f32_e32 v121, 0xbfb8aa3b, v121
	v_mul_f32_e32 v131, 0x3d372713, v158
	v_exp_f32_e32 v120, v120
	v_exp_f32_e32 v121, v121
	v_mul_f32_e32 v131, v158, v131
	v_fma_f32 v131, v158, v131, v158
	v_mul_f32_e32 v131, 0x3fcc422a, v131
	v_mul_f32_e32 v131, 0xbfb8aa3b, v131
	v_add_f32_e32 v120, 1.0, v120
	v_add_f32_e32 v121, 1.0, v121
	v_exp_f32_e32 v131, v131
	v_rcp_f32_e32 v120, v120
	v_rcp_f32_e32 v121, v121
	v_mul_f32_e32 v123, 0x3d372713, v161
	v_mul_f32_e32 v123, v161, v123
	v_mov_b32_e32 v130, v161
	v_fmac_f32_e32 v130, v130, v123
	v_add_f32_e32 v131, 1.0, v131
	v_mul_f32_e32 v123, 0x3fcc422a, v130
	v_mul_f32_e32 v130, 0x3d372713, v126
	v_rcp_f32_e32 v132, v131
	v_mul_f32_e32 v131, 0x3d372713, v127
	v_pk_mul_f32 v[124:125], v[124:125], v[120:121]
	v_mul_f32_e32 v120, 0x3d372713, v159
	v_mul_f32_e32 v130, v126, v130
	v_mul_f32_e32 v131, v127, v131
	v_mul_f32_e32 v120, v159, v120
	v_fma_f32 v130, v126, v130, v126
	v_fma_f32 v131, v127, v131, v127
	v_fma_f32 v120, v159, v120, v159
	v_mul_f32_e32 v130, 0x3fcc422a, v130
	v_mul_f32_e32 v131, 0x3fcc422a, v131
	v_mul_f32_e32 v120, 0x3fcc422a, v120
	v_mul_f32_e32 v123, 0xbfb8aa3b, v123
	v_mul_f32_e32 v130, 0xbfb8aa3b, v130
	v_mul_f32_e32 v131, 0xbfb8aa3b, v131
	v_mul_f32_e32 v120, 0xbfb8aa3b, v120
	v_exp_f32_e32 v123, v123
	v_exp_f32_e32 v130, v130
	v_exp_f32_e32 v131, v131
	v_exp_f32_e32 v120, v120
	v_add_f32_e32 v123, 1.0, v123
	v_add_f32_e32 v130, 1.0, v130
	v_add_f32_e32 v131, 1.0, v131
	v_add_f32_e32 v120, 1.0, v120
	v_rcp_f32_e32 v123, v123
	v_rcp_f32_e32 v130, v130
	v_rcp_f32_e32 v131, v131
	v_rcp_f32_e32 v133, v120
	v_pk_mul_f32 v[160:161], v[160:161], v[122:123]
	v_pk_mul_f32 v[126:127], v[126:127], v[130:131]
	v_pk_mul_f32 v[158:159], v[158:159], v[132:133]

.Lg1_epi:
	s_setprio 0
	s_nop 0
	s_nop 0
	s_nop 0
	s_nop 0
	s_nop 0
	s_nop 0
	s_waitcnt vmcnt(8)
	v_fmamk_f32 v132, v165, 0x3a800000, v235
	v_cmp_gt_f32_e32 vcc, s86, v132
	v_mul_f32_e32 v133, 0x4b800000, v132
	v_pk_mul_f32 v[126:127], v[118:119], v[126:127]
	v_cndmask_b32_e32 v132, v132, v133, vcc
	v_rsq_f32_e32 v132, v132
	v_pk_mul_f32 v[122:123], v[114:115], v[122:123]
	v_lshl_or_b32 v130, s0, 7, v157
	v_ashrrev_i32_e32 v131, 31, v130
	v_mul_f32_e32 v133, 0x45800000, v132
	v_cndmask_b32_e32 v132, v132, v133, vcc
	v_mul_f32_e32 v133, 0xbfb8aa3b, v132
	v_mul_f32_e32 v135, v133, v112
	v_exp_f32_e32 v135, v135
	v_mul_f32_e32 v134, v133, v116
	v_exp_f32_e32 v134, v134
	v_mul_f32_e32 v132, v132, v132
	v_add_f32_e32 v135, 1.0, v135
	v_rcp_f32_e32 v136, v135
	v_mul_f32_e32 v135, v133, v117
	v_exp_f32_e32 v135, v135
	v_add_f32_e32 v134, 1.0, v134
	v_rcp_f32_e32 v134, v134
	v_pk_mul_f32 v[116:117], v[116:117], v[124:125]
	v_add_f32_e32 v135, 1.0, v135
	v_rcp_f32_e32 v135, v135
	v_mul_f32_e32 v118, v133, v118
	v_mul_f32_e32 v119, v133, v119
	v_exp_f32_e32 v118, v118
	v_pk_mul_f32 v[124:125], v[132:133], v[134:135] op_sel_hi:[0,1]
	v_pk_mul_f32 v[116:117], v[124:125], v[116:117]
	v_mul_f32_e32 v124, v133, v113
	v_exp_f32_e32 v124, v124
	v_mul_f32_e32 v114, v133, v114
	v_exp_f32_e32 v119, v119
	v_mul_f32_e32 v115, v133, v115
	v_exp_f32_e32 v114, v114
	v_exp_f32_e32 v115, v115
	v_add_f32_e32 v124, 1.0, v124
	v_add_f32_e32 v118, 1.0, v118
	v_add_f32_e32 v119, 1.0, v119
	v_rcp_f32_e32 v137, v124
	v_rcp_f32_e32 v118, v118
	v_add_f32_e32 v114, 1.0, v114
	v_rcp_f32_e32 v119, v119
	v_add_f32_e32 v115, 1.0, v115
	v_rcp_f32_e32 v114, v114
	v_rcp_f32_e32 v115, v115
	v_pk_mul_f32 v[112:113], v[112:113], v[120:121]
	v_pk_mul_f32 v[120:121], v[132:133], v[136:137] op_sel_hi:[0,1]
	v_pk_mul_f32 v[118:119], v[132:133], v[118:119] op_sel_hi:[0,1]
	v_pk_mul_f32 v[112:113], v[120:121], v[112:113]
	v_pk_mul_f32 v[118:119], v[118:119], v[126:127]
	v_pk_mul_f32 v[114:115], v[132:133], v[114:115] op_sel_hi:[0,1]
	v_pk_mul_f32 v[114:115], v[114:115], v[122:123]
	v_cvt_pk_bf16_f32 v116, v116, v117
	v_cvt_pk_bf16_f32 v117, v118, v119
	v_cvt_pk_bf16_f32 v118, v112, v113
	v_mov_b64_e32 v[112:113], s[94:95]
	s_movk_i32 s9, 0x1600
	v_cvt_pk_bf16_f32 v119, v114, v115
	v_mad_i64_i32 v[120:121], s[0:1], v154, s9, v[112:113]
	v_lshlrev_b64 v[114:115], 1, v[130:131]
	v_lshl_add_u64 v[120:121], v[120:121], 0, v[114:115]
	global_store_dwordx4 v[120:121], v[116:119], off nt
	v_pk_mul_f32 v[106:107], v[98:99], v[106:107]
	v_pk_mul_f32 v[110:111], v[102:103], v[110:111]
	v_fmamk_f32 v116, v164, 0x3a800000, v235
	v_cmp_gt_f32_e32 vcc, s86, v116
	v_mul_f32_e32 v117, 0x4b800000, v116
	v_pk_mul_f32 v[90:91], v[82:83], v[90:91]
	v_cndmask_b32_e32 v116, v116, v117, vcc
	v_rsq_f32_e32 v116, v116
	v_pk_mul_f32 v[94:95], v[86:87], v[94:95]
	v_pk_mul_f32 v[74:75], v[66:67], v[74:75]
	v_pk_mul_f32 v[78:79], v[70:71], v[78:79]
	v_mul_f32_e32 v117, 0x45800000, v116
	v_cndmask_b32_e32 v116, v116, v117, vcc
	v_mul_f32_e32 v117, 0xbfb8aa3b, v116
	v_mul_f32_e32 v119, v117, v96
	v_exp_f32_e32 v119, v119
	v_mul_f32_e32 v118, v117, v100
	v_exp_f32_e32 v118, v118
	v_mul_f32_e32 v116, v116, v116
	v_add_f32_e32 v119, 1.0, v119
	v_rcp_f32_e32 v120, v119
	v_mul_f32_e32 v119, v117, v101
	v_exp_f32_e32 v119, v119
	v_add_f32_e32 v118, 1.0, v118
	v_rcp_f32_e32 v118, v118
	v_pk_mul_f32 v[100:101], v[100:101], v[108:109]
	v_add_f32_e32 v119, 1.0, v119
	v_rcp_f32_e32 v119, v119
	v_pk_mul_f32 v[58:59], v[50:51], v[58:59]
	v_pk_mul_f32 v[62:63], v[54:55], v[62:63]
	v_pk_mul_f32 v[42:43], v[34:35], v[42:43]
	v_pk_mul_f32 v[108:109], v[116:117], v[118:119] op_sel_hi:[0,1]
	v_pk_mul_f32 v[100:101], v[108:109], v[100:101]
	v_mul_f32_e32 v108, v117, v97
	v_exp_f32_e32 v108, v108
	v_pk_mul_f32 v[96:97], v[96:97], v[104:105]
	v_pk_mul_f32 v[46:47], v[38:39], v[46:47]
	v_pk_mul_f32 v[26:27], v[18:19], v[26:27]
	v_add_f32_e32 v108, 1.0, v108
	v_rcp_f32_e32 v121, v108
	v_or_b32_e32 v108, 16, v154
	v_pk_mul_f32 v[30:31], v[22:23], v[30:31]
	v_pk_mul_f32 v[10:11], v[2:3], v[10:11]
	v_pk_mul_f32 v[104:105], v[116:117], v[120:121] op_sel_hi:[0,1]
	v_pk_mul_f32 v[104:105], v[104:105], v[96:97]
	v_mul_f32_e32 v97, v117, v98
	v_exp_f32_e32 v97, v97
	v_mul_f32_e32 v96, v117, v102
	v_exp_f32_e32 v96, v96
	v_pk_mul_f32 v[14:15], v[6:7], v[14:15]
	v_add_f32_e32 v97, 1.0, v97
	v_rcp_f32_e32 v98, v97
	v_mul_f32_e32 v97, v117, v103
	v_exp_f32_e32 v97, v97
	v_add_f32_e32 v96, 1.0, v96
	v_rcp_f32_e32 v96, v96
	s_mov_b32 s20, s12
	v_add_f32_e32 v97, 1.0, v97
	v_rcp_f32_e32 v97, v97
	s_mov_b64 s[14:15], s[42:43]
	s_mov_b64 s[18:19], s[40:41]
	v_pk_mul_f32 v[96:97], v[116:117], v[96:97] op_sel_hi:[0,1]
	v_pk_mul_f32 v[102:103], v[96:97], v[110:111]
	v_mul_f32_e32 v96, v117, v99
	v_exp_f32_e32 v96, v96
	s_nop 0
	v_add_f32_e32 v96, 1.0, v96
	v_rcp_f32_e32 v99, v96
	s_nop 0
	v_pk_mul_f32 v[96:97], v[116:117], v[98:99] op_sel_hi:[0,1]
	v_pk_mul_f32 v[106:107], v[96:97], v[106:107]
	v_cvt_pk_bf16_f32 v96, v100, v101
	v_mad_i64_i32 v[100:101], s[0:1], v108, s9, v[112:113]
	v_cvt_pk_bf16_f32 v97, v102, v103
	v_cvt_pk_bf16_f32 v98, v104, v105
	v_cvt_pk_bf16_f32 v99, v106, v107
	v_lshl_add_u64 v[100:101], v[100:101], 0, v[114:115]
	global_store_dwordx4 v[100:101], v[96:99], off nt
	s_nop 1
	v_fmamk_f32 v96, v163, 0x3a800000, v235
	v_cmp_gt_f32_e32 vcc, s86, v96
	v_mul_f32_e32 v97, 0x4b800000, v96
	s_nop 0
	v_cndmask_b32_e32 v96, v96, v97, vcc
	v_rsq_f32_e32 v96, v96
	s_nop 0
	v_mul_f32_e32 v97, 0x45800000, v96
	v_cndmask_b32_e32 v96, v96, v97, vcc
	v_mul_f32_e32 v97, 0xbfb8aa3b, v96
	v_mul_f32_e32 v99, v97, v80
	v_exp_f32_e32 v99, v99
	v_mul_f32_e32 v98, v97, v84
	v_exp_f32_e32 v98, v98
	v_mul_f32_e32 v96, v96, v96
	v_add_f32_e32 v99, 1.0, v99
	v_rcp_f32_e32 v100, v99
	v_mul_f32_e32 v99, v97, v85
	v_exp_f32_e32 v99, v99
	v_add_f32_e32 v98, 1.0, v98
	v_rcp_f32_e32 v98, v98
	v_pk_mul_f32 v[84:85], v[84:85], v[92:93]
	v_add_f32_e32 v99, 1.0, v99
	v_rcp_f32_e32 v99, v99
	s_nop 0
	v_pk_mul_f32 v[92:93], v[96:97], v[98:99] op_sel_hi:[0,1]
	v_pk_mul_f32 v[84:85], v[92:93], v[84:85]
	v_mul_f32_e32 v92, v97, v81
	v_exp_f32_e32 v92, v92
	v_pk_mul_f32 v[80:81], v[80:81], v[88:89]
	v_add_f32_e32 v92, 1.0, v92
	v_rcp_f32_e32 v101, v92
	v_or_b32_e32 v92, 32, v154
	v_pk_mul_f32 v[88:89], v[96:97], v[100:101] op_sel_hi:[0,1]
	v_pk_mul_f32 v[88:89], v[88:89], v[80:81]
	v_mul_f32_e32 v81, v97, v82
	v_exp_f32_e32 v81, v81
	v_mul_f32_e32 v80, v97, v86
	v_exp_f32_e32 v80, v80
	v_add_f32_e32 v81, 1.0, v81
	v_rcp_f32_e32 v82, v81
	v_mul_f32_e32 v81, v97, v87
	v_exp_f32_e32 v81, v81
	v_add_f32_e32 v80, 1.0, v80
	v_rcp_f32_e32 v80, v80
	v_add_f32_e32 v81, 1.0, v81
	v_rcp_f32_e32 v81, v81
	s_nop 0
	v_pk_mul_f32 v[80:81], v[96:97], v[80:81] op_sel_hi:[0,1]
	v_pk_mul_f32 v[86:87], v[80:81], v[94:95]
	v_mul_f32_e32 v80, v97, v83
	v_exp_f32_e32 v80, v80
	s_nop 0
	v_add_f32_e32 v80, 1.0, v80
	v_rcp_f32_e32 v83, v80
	s_nop 0
	v_pk_mul_f32 v[80:81], v[96:97], v[82:83] op_sel_hi:[0,1]
	v_pk_mul_f32 v[90:91], v[80:81], v[90:91]
	v_cvt_pk_bf16_f32 v80, v84, v85
	v_mad_i64_i32 v[84:85], s[0:1], v92, s9, v[112:113]
	v_cvt_pk_bf16_f32 v81, v86, v87
	v_cvt_pk_bf16_f32 v82, v88, v89
	v_cvt_pk_bf16_f32 v83, v90, v91
	v_lshl_add_u64 v[84:85], v[84:85], 0, v[114:115]
	global_store_dwordx4 v[84:85], v[80:83], off nt
	s_nop 1
	v_fmamk_f32 v80, v162, 0x3a800000, v235
	v_cmp_gt_f32_e32 vcc, s86, v80
	v_mul_f32_e32 v81, 0x4b800000, v80
	s_nop 0
	v_cndmask_b32_e32 v80, v80, v81, vcc
	v_rsq_f32_e32 v80, v80
	s_nop 0
	v_mul_f32_e32 v81, 0x45800000, v80
	v_cndmask_b32_e32 v80, v80, v81, vcc
	v_mul_f32_e32 v81, 0xbfb8aa3b, v80
	v_mul_f32_e32 v83, v81, v64
	v_exp_f32_e32 v83, v83
	v_mul_f32_e32 v82, v81, v68
	v_exp_f32_e32 v82, v82
	v_mul_f32_e32 v80, v80, v80
	v_add_f32_e32 v83, 1.0, v83
	v_rcp_f32_e32 v84, v83
	v_mul_f32_e32 v83, v81, v69
	v_exp_f32_e32 v83, v83
	v_add_f32_e32 v82, 1.0, v82
	v_rcp_f32_e32 v82, v82
	v_pk_mul_f32 v[68:69], v[68:69], v[76:77]
	v_add_f32_e32 v83, 1.0, v83
	v_rcp_f32_e32 v83, v83
	s_nop 0
	v_pk_mul_f32 v[76:77], v[80:81], v[82:83] op_sel_hi:[0,1]
	v_pk_mul_f32 v[68:69], v[76:77], v[68:69]
	v_mul_f32_e32 v76, v81, v65
	v_exp_f32_e32 v76, v76
	v_pk_mul_f32 v[64:65], v[64:65], v[72:73]
	v_add_f32_e32 v76, 1.0, v76
	v_rcp_f32_e32 v85, v76
	v_or_b32_e32 v76, 48, v154
	v_pk_mul_f32 v[72:73], v[80:81], v[84:85] op_sel_hi:[0,1]
	v_pk_mul_f32 v[72:73], v[72:73], v[64:65]
	v_mul_f32_e32 v65, v81, v66
	v_exp_f32_e32 v65, v65
	v_mul_f32_e32 v64, v81, v70
	v_exp_f32_e32 v64, v64
	v_add_f32_e32 v65, 1.0, v65
	v_rcp_f32_e32 v66, v65
	v_mul_f32_e32 v65, v81, v71
	v_exp_f32_e32 v65, v65
	v_add_f32_e32 v64, 1.0, v64
	v_rcp_f32_e32 v64, v64
	v_add_f32_e32 v65, 1.0, v65
	v_rcp_f32_e32 v65, v65
	s_nop 0
	v_pk_mul_f32 v[64:65], v[80:81], v[64:65] op_sel_hi:[0,1]
	v_pk_mul_f32 v[70:71], v[64:65], v[78:79]
	v_mul_f32_e32 v64, v81, v67
	v_exp_f32_e32 v64, v64
	s_nop 0
	v_add_f32_e32 v64, 1.0, v64
	v_rcp_f32_e32 v67, v64
	s_nop 0
	v_pk_mul_f32 v[64:65], v[80:81], v[66:67] op_sel_hi:[0,1]
	v_pk_mul_f32 v[74:75], v[64:65], v[74:75]
	v_cvt_pk_bf16_f32 v64, v68, v69
	v_mad_i64_i32 v[68:69], s[0:1], v76, s9, v[112:113]
	v_cvt_pk_bf16_f32 v65, v70, v71
	v_cvt_pk_bf16_f32 v66, v72, v73
	v_cvt_pk_bf16_f32 v67, v74, v75
	v_lshl_add_u64 v[68:69], v[68:69], 0, v[114:115]
	global_store_dwordx4 v[68:69], v[64:67], off nt
	s_nop 1
	v_fmamk_f32 v64, v161, 0x3a800000, v235
	v_cmp_gt_f32_e32 vcc, s86, v64
	v_mul_f32_e32 v66, 0x4b800000, v64
	v_add_u32_e32 v65, 0x80, v154
	v_cndmask_b32_e32 v64, v64, v66, vcc
	v_rsq_f32_e32 v64, v64
	s_nop 0
	v_mul_f32_e32 v66, 0x45800000, v64
	v_cndmask_b32_e32 v64, v64, v66, vcc
	v_mul_f32_e32 v70, 0xbfb8aa3b, v64
	v_mul_f32_e32 v67, v70, v48
	v_exp_f32_e32 v67, v67
	v_mul_f32_e32 v66, v70, v52
	v_exp_f32_e32 v66, v66
	v_mul_f32_e32 v64, v64, v64
	v_add_f32_e32 v67, 1.0, v67
	v_rcp_f32_e32 v68, v67
	v_mul_f32_e32 v67, v70, v53
	v_exp_f32_e32 v67, v67
	v_add_f32_e32 v66, 1.0, v66
	v_rcp_f32_e32 v66, v66
	v_pk_mul_f32 v[52:53], v[52:53], v[60:61]
	v_add_f32_e32 v67, 1.0, v67
	v_rcp_f32_e32 v67, v67
	s_nop 0
	v_pk_mul_f32 v[60:61], v[64:65], v[66:67] op_sel_hi:[0,1]
	v_pk_mul_f32 v[52:53], v[60:61], v[52:53]
	v_mul_f32_e32 v60, v70, v49
	v_exp_f32_e32 v60, v60
	v_pk_mul_f32 v[48:49], v[48:49], v[56:57]
	v_add_f32_e32 v60, 1.0, v60
	v_rcp_f32_e32 v69, v60
	s_nop 0
	v_pk_mul_f32 v[56:57], v[64:65], v[68:69] op_sel_hi:[0,1]
	v_pk_mul_f32 v[56:57], v[56:57], v[48:49]
	v_mul_f32_e32 v49, v70, v50
	v_exp_f32_e32 v49, v49
	v_mul_f32_e32 v48, v70, v54
	v_exp_f32_e32 v48, v48
	v_add_f32_e32 v49, 1.0, v49
	v_rcp_f32_e32 v50, v49
	v_mul_f32_e32 v49, v70, v55
	v_exp_f32_e32 v49, v49
	v_add_f32_e32 v48, 1.0, v48
	v_rcp_f32_e32 v48, v48
	v_add_f32_e32 v49, 1.0, v49
	v_rcp_f32_e32 v49, v49
	s_nop 0
	v_pk_mul_f32 v[48:49], v[64:65], v[48:49] op_sel_hi:[0,1]
	v_pk_mul_f32 v[54:55], v[48:49], v[62:63]
	v_mul_f32_e32 v48, v70, v51
	v_exp_f32_e32 v48, v48
	s_nop 0
	v_add_f32_e32 v48, 1.0, v48
	v_rcp_f32_e32 v51, v48
	s_nop 0
	v_pk_mul_f32 v[48:49], v[64:65], v[50:51] op_sel_hi:[0,1]
	v_pk_mul_f32 v[58:59], v[48:49], v[58:59]
	v_cvt_pk_bf16_f32 v48, v52, v53
	v_mad_i64_i32 v[52:53], s[0:1], v65, s9, v[112:113]
	v_cvt_pk_bf16_f32 v49, v54, v55
	v_cvt_pk_bf16_f32 v50, v56, v57
	v_cvt_pk_bf16_f32 v51, v58, v59
	v_lshl_add_u64 v[52:53], v[52:53], 0, v[114:115]
	global_store_dwordx4 v[52:53], v[48:51], off nt
	s_nop 1
	v_fmamk_f32 v48, v160, 0x3a800000, v235
	v_cmp_gt_f32_e32 vcc, s86, v48
	v_mul_f32_e32 v49, 0x4b800000, v48
	s_nop 0
	v_cndmask_b32_e32 v48, v48, v49, vcc
	v_rsq_f32_e32 v48, v48
	s_nop 0
	v_mul_f32_e32 v49, 0x45800000, v48
	v_cndmask_b32_e32 v48, v48, v49, vcc
	v_mul_f32_e32 v49, 0xbfb8aa3b, v48
	v_mul_f32_e32 v51, v49, v32
	v_exp_f32_e32 v51, v51
	v_mul_f32_e32 v50, v49, v36
	v_exp_f32_e32 v50, v50
	v_mul_f32_e32 v48, v48, v48
	v_add_f32_e32 v51, 1.0, v51
	v_rcp_f32_e32 v52, v51
	v_mul_f32_e32 v51, v49, v37
	v_exp_f32_e32 v51, v51
	v_add_f32_e32 v50, 1.0, v50
	v_rcp_f32_e32 v50, v50
	v_pk_mul_f32 v[36:37], v[36:37], v[44:45]
	v_add_f32_e32 v51, 1.0, v51
	v_rcp_f32_e32 v51, v51
	s_nop 0
	v_pk_mul_f32 v[44:45], v[48:49], v[50:51] op_sel_hi:[0,1]
	v_pk_mul_f32 v[36:37], v[44:45], v[36:37]
	v_mul_f32_e32 v44, v49, v33
	v_exp_f32_e32 v44, v44
	v_pk_mul_f32 v[32:33], v[32:33], v[40:41]
	v_add_f32_e32 v44, 1.0, v44
	v_rcp_f32_e32 v53, v44
	v_add_u32_e32 v44, 0x90, v154
	v_pk_mul_f32 v[40:41], v[48:49], v[52:53] op_sel_hi:[0,1]
	v_pk_mul_f32 v[40:41], v[40:41], v[32:33]
	v_mul_f32_e32 v33, v49, v34
	v_exp_f32_e32 v33, v33
	v_mul_f32_e32 v32, v49, v38
	v_exp_f32_e32 v32, v32
	v_add_f32_e32 v33, 1.0, v33
	v_rcp_f32_e32 v34, v33
	v_mul_f32_e32 v33, v49, v39
	v_exp_f32_e32 v33, v33
	v_add_f32_e32 v32, 1.0, v32
	v_rcp_f32_e32 v32, v32
	v_add_f32_e32 v33, 1.0, v33
	v_rcp_f32_e32 v33, v33
	s_nop 0
	v_pk_mul_f32 v[32:33], v[48:49], v[32:33] op_sel_hi:[0,1]
	v_pk_mul_f32 v[38:39], v[32:33], v[46:47]
	v_mul_f32_e32 v32, v49, v35
	v_exp_f32_e32 v32, v32
	s_nop 0
	v_add_f32_e32 v32, 1.0, v32
	v_rcp_f32_e32 v35, v32
	s_nop 0
	v_pk_mul_f32 v[32:33], v[48:49], v[34:35] op_sel_hi:[0,1]
	v_pk_mul_f32 v[42:43], v[32:33], v[42:43]
	v_cvt_pk_bf16_f32 v32, v36, v37
	v_mad_i64_i32 v[36:37], s[0:1], v44, s9, v[112:113]
	v_cvt_pk_bf16_f32 v33, v38, v39
	v_cvt_pk_bf16_f32 v34, v40, v41
	v_cvt_pk_bf16_f32 v35, v42, v43
	v_lshl_add_u64 v[36:37], v[36:37], 0, v[114:115]
	global_store_dwordx4 v[36:37], v[32:35], off nt
	s_nop 1
	v_fmamk_f32 v32, v159, 0x3a800000, v235
	v_cmp_gt_f32_e32 vcc, s86, v32
	v_mul_f32_e32 v33, 0x4b800000, v32
	s_nop 0
	v_cndmask_b32_e32 v32, v32, v33, vcc
	v_rsq_f32_e32 v32, v32
	s_nop 0
	v_mul_f32_e32 v33, 0x45800000, v32
	v_cndmask_b32_e32 v32, v32, v33, vcc
	v_mul_f32_e32 v33, 0xbfb8aa3b, v32
	v_mul_f32_e32 v35, v33, v16
	v_exp_f32_e32 v35, v35
	v_mul_f32_e32 v34, v33, v20
	v_exp_f32_e32 v34, v34
	v_mul_f32_e32 v32, v32, v32
	v_add_f32_e32 v35, 1.0, v35
	v_rcp_f32_e32 v36, v35
	v_mul_f32_e32 v35, v33, v21
	v_exp_f32_e32 v35, v35
	v_add_f32_e32 v34, 1.0, v34
	v_rcp_f32_e32 v34, v34
	v_pk_mul_f32 v[20:21], v[20:21], v[28:29]
	v_add_f32_e32 v35, 1.0, v35
	v_rcp_f32_e32 v35, v35
	s_nop 0
	v_pk_mul_f32 v[28:29], v[32:33], v[34:35] op_sel_hi:[0,1]
	v_pk_mul_f32 v[20:21], v[28:29], v[20:21]
	v_mul_f32_e32 v28, v33, v17
	v_exp_f32_e32 v28, v28
	v_pk_mul_f32 v[16:17], v[16:17], v[24:25]
	v_add_f32_e32 v28, 1.0, v28
	v_rcp_f32_e32 v37, v28
	v_add_u32_e32 v28, 0xa0, v154
	v_pk_mul_f32 v[24:25], v[32:33], v[36:37] op_sel_hi:[0,1]
	v_pk_mul_f32 v[24:25], v[24:25], v[16:17]
	v_mul_f32_e32 v17, v33, v18
	v_exp_f32_e32 v17, v17
	v_mul_f32_e32 v16, v33, v22
	v_exp_f32_e32 v16, v16
	v_add_f32_e32 v17, 1.0, v17
	v_rcp_f32_e32 v18, v17
	v_mul_f32_e32 v17, v33, v23
	v_exp_f32_e32 v17, v17
	v_add_f32_e32 v16, 1.0, v16
	v_rcp_f32_e32 v16, v16
	v_add_f32_e32 v17, 1.0, v17
	v_rcp_f32_e32 v17, v17
	s_nop 0
	v_pk_mul_f32 v[16:17], v[32:33], v[16:17] op_sel_hi:[0,1]
	v_pk_mul_f32 v[22:23], v[16:17], v[30:31]
	v_mul_f32_e32 v16, v33, v19
	v_exp_f32_e32 v16, v16
	s_nop 0
	v_add_f32_e32 v16, 1.0, v16
	v_rcp_f32_e32 v19, v16
	s_nop 0
	v_pk_mul_f32 v[16:17], v[32:33], v[18:19] op_sel_hi:[0,1]
	v_pk_mul_f32 v[26:27], v[16:17], v[26:27]
	v_cvt_pk_bf16_f32 v16, v20, v21
	v_mad_i64_i32 v[20:21], s[0:1], v28, s9, v[112:113]
	v_cvt_pk_bf16_f32 v17, v22, v23
	v_cvt_pk_bf16_f32 v18, v24, v25
	v_cvt_pk_bf16_f32 v19, v26, v27
	v_lshl_add_u64 v[20:21], v[20:21], 0, v[114:115]
	global_store_dwordx4 v[20:21], v[16:19], off nt
	s_nop 1
	v_fmamk_f32 v16, v155, 0x3a800000, v235
	v_cmp_gt_f32_e32 vcc, s86, v16
	v_mul_f32_e32 v17, 0x4b800000, v16
	s_nop 0
	v_cndmask_b32_e32 v16, v16, v17, vcc
	v_rsq_f32_e32 v16, v16
	s_nop 0
	v_mul_f32_e32 v17, 0x45800000, v16
	v_cndmask_b32_e32 v16, v16, v17, vcc
	v_mul_f32_e32 v17, 0xbfb8aa3b, v16
	v_mul_f32_e32 v19, v17, v0
	v_exp_f32_e32 v19, v19
	v_mul_f32_e32 v18, v17, v4
	v_exp_f32_e32 v18, v18
	v_mul_f32_e32 v16, v16, v16
	v_add_f32_e32 v19, 1.0, v19
	v_rcp_f32_e32 v20, v19
	v_mul_f32_e32 v19, v17, v5
	v_exp_f32_e32 v19, v19
	v_add_f32_e32 v18, 1.0, v18
	v_rcp_f32_e32 v18, v18
	v_pk_mul_f32 v[4:5], v[4:5], v[12:13]
	v_add_f32_e32 v19, 1.0, v19
	v_rcp_f32_e32 v19, v19
	s_and_b64 vcc, exec, s[38:39]
	v_pk_mul_f32 v[12:13], v[16:17], v[18:19] op_sel_hi:[0,1]
	v_pk_mul_f32 v[4:5], v[12:13], v[4:5]
	v_mul_f32_e32 v12, v17, v1
	v_exp_f32_e32 v12, v12
	v_pk_mul_f32 v[0:1], v[0:1], v[8:9]
	v_add_f32_e32 v12, 1.0, v12
	v_rcp_f32_e32 v21, v12
	v_add_u32_e32 v12, 0xb0, v154
	v_pk_mul_f32 v[8:9], v[16:17], v[20:21] op_sel_hi:[0,1]
	v_pk_mul_f32 v[8:9], v[8:9], v[0:1]
	v_mul_f32_e32 v1, v17, v2
	v_exp_f32_e32 v1, v1
	v_mul_f32_e32 v0, v17, v6
	v_exp_f32_e32 v0, v0
	v_add_f32_e32 v1, 1.0, v1
	v_rcp_f32_e32 v2, v1
	v_mul_f32_e32 v1, v17, v7
	v_exp_f32_e32 v1, v1
	v_add_f32_e32 v0, 1.0, v0
	v_rcp_f32_e32 v0, v0
	v_add_f32_e32 v1, 1.0, v1
	v_rcp_f32_e32 v1, v1
	s_nop 0
	v_pk_mul_f32 v[0:1], v[16:17], v[0:1] op_sel_hi:[0,1]
	v_pk_mul_f32 v[6:7], v[0:1], v[14:15]
	v_mul_f32_e32 v0, v17, v3
	v_exp_f32_e32 v0, v0
	s_nop 0
	v_add_f32_e32 v0, 1.0, v0
	v_rcp_f32_e32 v3, v0
	s_nop 0
	v_pk_mul_f32 v[0:1], v[16:17], v[2:3] op_sel_hi:[0,1]
	v_pk_mul_f32 v[10:11], v[0:1], v[10:11]
	v_cvt_pk_bf16_f32 v0, v4, v5
	v_mad_i64_i32 v[4:5], s[0:1], v12, s9, v[112:113]
	v_cvt_pk_bf16_f32 v1, v6, v7
	v_cvt_pk_bf16_f32 v2, v8, v9
	v_cvt_pk_bf16_f32 v3, v10, v11
	v_lshl_add_u64 v[4:5], v[4:5], 0, v[114:115]
	s_mov_b32 s0, s8
	global_store_dwordx4 v[4:5], v[0:3], off nt
	s_cbranch_vccz .LBB0_388
	s_waitcnt vmcnt(0)
	v_readlane_b32 s20, v255, 27
